# attention work queues: workgroup takes 8 consecutive items sharing one K/V stream (L1 reuse)
# speedup vs baseline: 1.1422x; 1.0102x over previous
; #define TIDX get_tid_()
; DI float bf2f(bf16_t b) { return __uint_as_float(((unsigned)b) << 16); }
; DI int crow(int i, int h) { return (i & 3) + 8 * (i >> 2) + 4 * h; }
; DI void nsa_main_item(const Params& p, int b, int head, int qb, const unsigned char* blut, const float* tbl) {
;   const int lane = TIDX & 63, r = lane & 31, h = lane >> 5;
;   const int g = head / 3, bg = b * 2 + g;
;   const int t = qb * 32 + r;
;   const float* tblh = tbl + head * 32;
;   bf16x8 qf[4];
;   load_q(qf, (const bf16_t*)(p.ws + OFF_QN) + (size_t)(b * 4096 + t) * 384 + head * 64 + 8 * h);
;   const unsigned long long selm = ((const unsigned long long*)(p.ws + OFF_SELM))[(size_t)bg * 4096 + t];
;   const float* gates = (const float*)(p.ws + OFF_GATES) + (size_t)(b * 4096 + t) * 18 + head * 3;
;   const float g1 = gates[1];
;   f32x16 y0, y1;
;   {
;     const bf16_t* oc = (const bf16_t*)(p.ws + OFF_OC) + (size_t)(b * 4096 + t) * 384 + head * 64;
;     const bf16_t* yw = (const bf16_t*)(p.ws + OFF_Y) + (size_t)(b * 4096 + t) * 768 + head * 64;
; #pragma unroll
;     for (int i = 0; i < 16; ++i) { y0[i] = bf2f(oc[crow(i, h)]) + bf2f(yw[crow(i, h)]); y1[i] = bf2f(oc[32 + crow(i, h)]) + bf2f(yw[32 + crow(i, h)]); }
;   }
;     ...
;   for (;;) {
;     const int item = wave_fetch(ctr);
;     if (item >= 128 * 48) break;
;     const int qb = 127 - item / 48, sub = item % 48;
;     nsa_main_item(p, sub / 6, sub % 6, qb, blut, tbl);
.LBB0_703:
	s_barrier
	v_mov_b32_e32 v0, 0x1900
	v_cmp_eq_u32_e32 vcc, 0, v129
	s_and_saveexec_b64 s[8:9], vcc
	s_cbranch_execz .LfY_skip
	v_mov_b32_e32 v1, 8
	global_atomic_add v1, v131, v1, s[10:11] sc0
	s_waitcnt vmcnt(0)
	ds_write_b32 v0, v1
	s_waitcnt lgkmcnt(0)
.LfY_skip:
	s_or_b64 exec, exec, s[8:9]
	s_barrier
	ds_read_b32 v0, v0
	v_lshrrev_b32_e32 v1, 6, v129
	s_waitcnt lgkmcnt(0)
	v_add_u32_e32 v0, v0, v1
	s_movk_i32 s8, 0x300
	s_waitcnt lgkmcnt(0)
	v_cmp_gt_i32_e32 vcc, s8, v0
	s_mov_b64 s[8:9], -1
	s_and_saveexec_b64 s[14:15], vcc
	s_cbranch_execz .LBB0_702
	v_lshrrev_b32_e32 v1, 4, v0
	v_lshlrev_b32_e32 v1, 3, v1
	v_and_b32_e32 v2, 7, v0
	v_add_u32_e32 v1, v1, v2
	v_bfe_u32 v2, v0, 3, 1
	v_mul_u32_u24_e32 v2, 3, v2
	v_add_u32_e32 v2, v2, v1
	v_mul_u32_u24_e32 v0, 0x5556, v1
	v_lshrrev_b32_e32 v0, 16, v0
	v_mul_u32_u24_e32 v0, 45, v0
	v_add3_u32 v0, v0, v2, s101
	s_mov_b32 s8, 0xd5555555
	v_mul_hi_i32 v1, v0, s8
	v_lshrrev_b32_e32 v2, 31, v1
	v_ashrrev_i32_e32 v1, 3, v1
	s_movk_i32 s8, 0x7f
	v_add3_u32 v217, v1, v2, s8
	s_mov_b32 s8, 0x2aaaaaab
	v_mul_hi_i32 v1, v0, s8
	v_lshrrev_b32_e32 v2, 31, v1
	v_lshrrev_b32_e32 v1, 3, v1
	v_add_u32_e32 v1, v1, v2
	v_mul_lo_u32 v1, v1, 48
	v_sub_u32_e32 v0, v0, v1
	v_mul_lo_u16_e32 v1, 43, v0
	v_lshrrev_b16_e32 v2, 15, v1
	v_add_u16_sdwa v1, v1, v2 dst_sel:DWORD dst_unused:UNUSED_PAD src0_sel:BYTE_1 src1_sel:DWORD
	v_bfe_i32 v2, v1, 0, 8
	v_mul_lo_u16_e32 v1, 6, v1
	v_sub_u16_e32 v0, v0, v1
	v_bfe_i32 v28, v0, 0, 8
	v_mov_b32_e32 v0, v129
	v_lshlrev_b32_e32 v31, 5, v217
	v_and_b32_e32 v29, 31, v0
	v_bfe_u32 v30, v0, 5, 1
	v_mul_lo_u16_e32 v0, 0x56, v28
	v_lshrrev_b16_e32 v1, 15, v0
	v_add_u16_sdwa v0, v0, v1 dst_sel:DWORD dst_unused:UNUSED_PAD src0_sel:BYTE_1 src1_sel:DWORD
	v_readlane_b32 s8, v253, 13
	v_bfe_i32 v0, v0, 0, 8
	v_or_b32_e32 v10, v29, v31
	v_readlane_b32 s9, v253, 14
	v_lshl_add_u32 v8, v2, 1, v0
	v_lshl_add_u32 v22, v2, 12, v10
	v_mov_b64_e32 v[0:1], s[8:9]
	s_movk_i32 s23, 0x300
	v_mad_i64_i32 v[0:1], s[8:9], v22, s23, v[0:1]
	v_lshlrev_b32_e32 v2, 6, v28
	v_ashrrev_i32_e32 v3, 31, v2
	v_readlane_b32 s8, v253, 23
	v_lshlrev_b64 v[2:3], 1, v[2:3]
	v_readlane_b32 s9, v253, 24
	v_lshl_add_u64 v[4:5], v[0:1], 0, v[2:3]
	v_lshlrev_b32_e32 v130, 3, v30
	v_mov_b64_e32 v[0:1], s[8:9]
	v_mad_i64_i32 v[0:1], s[8:9], v22, s23, v[0:1]
	v_readlane_b32 s8, v253, 19
	v_readlane_b32 s9, v253, 20
	v_lshl_add_u64 v[0:1], v[0:1], 0, v[2:3]
	v_ashrrev_i32_e32 v9, 31, v8
	v_mov_b64_e32 v[6:7], s[8:9]
	s_movk_i32 s8, 0x600
	v_mad_i64_i32 v[6:7], s[8:9], v22, s8, v[6:7]
	v_lshl_add_u64 v[2:3], v[6:7], 0, v[2:3]
	v_lshl_add_u64 v[12:13], v[0:1], 0, v[130:131]
	v_readlane_b32 s8, v253, 25
	v_lshlrev_b32_e32 v0, 3, v29
	v_lshl_add_u64 v[132:133], v[2:3], 0, v[130:131]
	v_lshlrev_b64 v[14:15], 19, v[8:9]
	v_readlane_b32 s9, v253, 26
	v_lshl_or_b32 v130, v30, 8, v0
	v_lshlrev_b32_e32 v20, 1, v130
	v_lshl_add_u64 v[16:17], s[8:9], 0, v[14:15]
	v_mov_b32_e32 v21, v131
	v_lshl_add_u64 v[148:149], v[16:17], 0, v[20:21]
	global_load_dwordx4 v[0:3], v[148:149], off
	v_lshlrev_b32_e32 v6, 4, v30
	v_mov_b32_e32 v7, v131
	v_lshl_add_u64 v[4:5], v[4:5], 0, v[6:7]
	global_load_dwordx4 v[80:83], v[4:5], off
	v_mov_b64_e32 v[6:7], s[34:35]
	s_movk_i32 s8, 0x48
	v_mad_i64_i32 v[6:7], s[8:9], v22, s8, v[6:7]
	v_mul_i32_i24_e32 v22, 3, v28
	v_ashrrev_i32_e32 v23, 31, v22
	v_cmp_eq_u32_e32 vcc, 0, v217
	v_lshl_add_u64 v[6:7], v[22:23], 2, v[6:7]
	s_mov_b32 s8, 0x165c4000
	v_cndmask_b32_e64 v18, v197, 0, vcc
	v_add_co_u32_e32 v22, vcc, s8, v6
	v_readlane_b32 s8, v253, 21
	s_nop 0
	v_addc_co_u32_e32 v23, vcc, 0, v7, vcc
	global_load_dwordx4 v[84:87], v[4:5], off offset:32
	global_load_dwordx4 v[88:91], v[4:5], off offset:64
	global_load_dwordx4 v[92:95], v[4:5], off offset:96
	global_load_dwordx2 v[136:137], v[12:13], off offset:64
	global_load_dwordx2 v[144:145], v[12:13], off offset:80
	global_load_dwordx2 v[150:151], v[12:13], off offset:32
	global_load_dwordx2 v[160:161], v[12:13], off offset:48
	global_load_dwordx2 v[134:135], v[132:133], off
	global_load_dwordx2 v[142:143], v[132:133], off offset:16
	global_load_dwordx2 v[152:153], v[132:133], off offset:32
	global_load_dwordx2 v[162:163], v[132:133], off offset:48
	global_load_dwordx2 v[154:155], v[12:13], off offset:96
	global_load_dwordx2 v[164:165], v[12:13], off offset:112
	global_load_dwordx4 v[4:7], v[148:149], off offset:1024
	global_load_dwordx2 v[138:139], v[132:133], off offset:64
	global_load_dwordx2 v[146:147], v[132:133], off offset:80
	global_load_dwordx2 v[158:159], v[132:133], off offset:96
	global_load_dwordx2 v[166:167], v[132:133], off offset:112
	v_lshlrev_b64 v[8:9], 15, v[8:9]
	v_readlane_b32 s9, v253, 22
	v_mov_b32_e32 v11, v131
	v_mov_b32_e32 v19, v131
	v_lshl_add_u64 v[8:9], s[8:9], 0, v[8:9]
	v_lshl_add_u64 v[24:25], v[10:11], 3, v[8:9]
	v_lshl_add_u64 v[26:27], v[16:17], 0, v[18:19]
	global_load_dwordx4 v[8:11], v[148:149], off offset:2048
	global_load_dwordx2 v[168:169], v[24:25], off
	global_load_dword v218, v[22:23], off offset:4
	global_load_dwordx2 v[140:141], v[12:13], off
	global_load_dwordx2 v[156:157], v[12:13], off offset:16
	global_load_dwordx4 v[16:19], v[148:149], off offset:3072
	v_readlane_b32 s8, v253, 27
	v_readlane_b32 s9, v253, 28
	v_lshl_add_u64 v[12:13], v[26:27], 0, v[20:21]
	global_load_dwordx4 v[108:111], v[12:13], off offset:3072
	global_load_dwordx4 v[104:107], v[12:13], off offset:2048
	global_load_dwordx4 v[100:103], v[12:13], off offset:1024
	global_load_dwordx4 v[96:99], v[12:13], off
	v_lshl_add_u64 v[14:15], s[8:9], 0, v[14:15]
	v_lshl_add_u64 v[170:171], v[14:15], 0, v[130:131]
	global_load_dwordx2 v[114:115], v[170:171], off offset:3584
	global_load_dwordx2 v[112:113], v[170:171], off offset:3072
	global_load_dwordx2 v[118:119], v[170:171], off offset:2560
	global_load_dwordx2 v[116:117], v[170:171], off offset:2048
	global_load_dwordx2 v[122:123], v[170:171], off offset:1536
	global_load_dwordx2 v[120:121], v[170:171], off offset:1024
	global_load_dwordx2 v[126:127], v[170:171], off offset:512
	global_load_dwordx2 v[124:125], v[170:171], off
	s_mov_b32 s56, 0
	s_mov_b32 s57, s56
	s_mov_b32 s58, s56
	s_mov_b32 s59, s56
	s_mov_b32 s60, s56
	s_mov_b32 s61, s56
	s_mov_b32 s62, s56
	s_mov_b32 s63, s56
	s_mov_b32 s64, s56
	s_mov_b32 s65, s56
	s_mov_b32 s66, s56
	s_mov_b32 s67, s56
	s_mov_b32 s68, s56
	s_mov_b32 s69, s56
	s_waitcnt vmcnt(36)
; #define MFMA32(a, b, c) __builtin_amdgcn_mfma_f32_32x32x16_bf16((a), (b), (c), 0, 0, 0)
; template <class KP, class VP, class ACT, class FILL>
; DI void attn_loop(AttnSt& st, const bf16x8 (&qf)[4], int k0, int k1, size_t vstride, KP kp, VP vp, ACT act, FILL fill) {
;   KVT cur, nxt;
;   {
;     KVT t0; load_kv(t0, kp(k0), vp(k0), vstride);
; #pragma unroll
;     for (int i = 0; i < 8; ++i) cur.v[i] = t0.v[i];
; #pragma unroll
;     for (int i = 0; i < 4; ++i) cur.k[i] = t0.k[i];
;   }
;   f32x16 s_cur;
;   { const float z = 0.f;
; #pragma unroll
;     for (int i = 0; i < 16; ++i) s_cur[i] = z; }
; #pragma unroll
;   for (int ss = 0; ss < 4; ++ss) s_cur = MFMA32(cur.k[ss], qf[ss], s_cur);
;   {
;     const int kn = (k0 < k1) ? k0 + 1 : k1;
;     const bf16_t* krow = kp(kn);
; #pragma unroll
;     for (int ss = 0; ss < 4; ++ss) nxt.k[ss] = *(const bf16x8*)(krow + 512 * ss);
;   }
;   for (int kt = k0; kt <= k1; ++kt) {
;     const int kn = (kt < k1) ? kt + 1 : k1;
;     const int kn2 = (kt + 2 <= k1) ? kt + 2 : k1;
;     {
;       const bf16_t* v0 = vp(kn);
; #pragma unroll
;       for (int j = 0; j < 8; ++j) nxt.v[j] = *(const s16x4*)(v0 + 256 * j);
;     }
;     bf16x8 k2[4];
;     {
;       const bf16_t* krow = kp(kn2);
; #pragma unroll
;       for (int ss = 0; ss < 4; ++ss) k2[ss] = *(const bf16x8*)(krow + 512 * ss);
;     }
	v_mfma_f32_32x32x16_bf16 v[48:63], v[0:3], v[80:83], 0
	s_mov_b32 s70, s56
	s_mov_b32 s71, s56
	v_lshlrev_b32_e32 v20, 2, v30
	v_lshl_add_u32 v219, v28, 7, 0
	v_subrev_u32_e32 v220, 31, v31
	v_sub_u32_e32 v221, v29, v20
	v_mov_b32_e32 v222, 0
	s_waitcnt vmcnt(22)
	v_mfma_f32_32x32x16_bf16 v[48:63], v[4:7], v[84:87], v[48:63]
	v_mov_b32_e32 v223, 0xff800000
	s_waitcnt vmcnt(17)
	v_mfma_f32_32x32x16_bf16 v[48:63], v[8:11], v[88:91], v[48:63]
	v_mov_b64_e32 v[0:1], s[56:57]
	v_mov_b64_e32 v[14:15], s[70:71]
	v_mov_b64_e32 v[2:3], s[58:59]
	v_mov_b64_e32 v[4:5], s[60:61]
	v_mov_b64_e32 v[6:7], s[62:63]
	v_mov_b64_e32 v[8:9], s[64:65]
	v_mov_b64_e32 v[10:11], s[66:67]
	s_waitcnt vmcnt(12)
	v_mfma_f32_32x32x16_bf16 v[48:63], v[16:19], v[92:95], v[48:63]
	v_mov_b64_e32 v[12:13], s[68:69]
	v_mov_b64_e32 v[30:31], v[14:15]
	s_mov_b64 s[58:59], 0
	v_mov_b64_e32 v[28:29], v[12:13]
	v_mov_b64_e32 v[26:27], v[10:11]
	v_mov_b64_e32 v[24:25], v[8:9]
	v_mov_b64_e32 v[22:23], v[6:7]
	v_mov_b64_e32 v[20:21], v[4:5]
	v_mov_b64_e32 v[18:19], v[2:3]
	v_mov_b64_e32 v[16:17], v[0:1]
	s_waitcnt vmcnt(0)
	v_readfirstlane_b32 s60, v217
	s_mov_b32 s56, 0
	s_mov_b32 s23, 0
	s_min_u32 s24, s23, s60
	s_lshl_b32 s26, s24, 12
	s_mov_b32 s27, 0
	v_lshl_add_u64 v[248:249], v[148:149], 0, s[26:27]
	global_load_dwordx4 v[96:99], v[248:249], off
	global_load_dwordx4 v[100:103], v[248:249], off offset:1024
	global_load_dwordx4 v[104:107], v[248:249], off offset:2048
	global_load_dwordx4 v[108:111], v[248:249], off offset:3072
	s_mov_b32 s23, 1
	s_min_u32 s24, s23, s60
	s_lshl_b32 s26, s24, 12
	s_mov_b32 s27, 0
	v_lshl_add_u64 v[248:249], v[148:149], 0, s[26:27]
	global_load_dwordx4 v[112:115], v[248:249], off
	global_load_dwordx4 v[116:119], v[248:249], off offset:1024
	global_load_dwordx4 v[120:123], v[248:249], off offset:2048
	global_load_dwordx4 v[124:127], v[248:249], off offset:3072
	s_mov_b32 s23, 0
	s_min_u32 s24, s23, s60
	s_lshl_b32 s26, s24, 12
	s_mov_b32 s27, 0
	v_lshl_add_u64 v[250:251], v[170:171], 0, s[26:27]
	global_load_dwordx2 v[64:65], v[250:251], off
	global_load_dwordx2 v[66:67], v[250:251], off offset:512
	global_load_dwordx2 v[68:69], v[250:251], off offset:1024
	global_load_dwordx2 v[70:71], v[250:251], off offset:1536
	global_load_dwordx2 v[72:73], v[250:251], off offset:2048
	global_load_dwordx2 v[74:75], v[250:251], off offset:2560
	global_load_dwordx2 v[76:77], v[250:251], off offset:3072
	global_load_dwordx2 v[78:79], v[250:251], off offset:3584
	s_mov_b32 s23, 1
	s_min_u32 s24, s23, s60
	s_lshl_b32 s26, s24, 12
	s_mov_b32 s27, 0
	v_lshl_add_u64 v[250:251], v[170:171], 0, s[26:27]
	global_load_dwordx2 v[172:173], v[250:251], off
	global_load_dwordx2 v[174:175], v[250:251], off offset:512
	global_load_dwordx2 v[176:177], v[250:251], off offset:1024
	global_load_dwordx2 v[178:179], v[250:251], off offset:1536
	global_load_dwordx2 v[180:181], v[250:251], off offset:2048
	global_load_dwordx2 v[182:183], v[250:251], off offset:2560
	global_load_dwordx2 v[184:185], v[250:251], off offset:3072
	global_load_dwordx2 v[186:187], v[250:251], off offset:3584
	v_lshrrev_b32_e32 v246, 6, v129
	v_mul_u32_u24_e32 v246, 6912, v246
	v_add_u32_e32 v242, 8192, v246
	v_and_b32_e32 v246, 63, v129
	v_add_u32_e32 v224, -64, v246
	v_mov_b32_e32 v224, 0
	v_mov_b32_e32 v225, v246
	v_add_u32_e32 v226, 64, v246
	v_add_u32_e32 v227, 128, v246
	v_add_u32_e32 v228, 192, v246
	v_add_u32_e32 v229, 256, v246
	v_add_u32_e32 v230, 320, v246
	v_add_u32_e32 v231, 384, v246
	v_add_u32_e32 v232, 448, v246
	ds_read_u8 v224, v224
	ds_read_u8 v225, v225
	ds_read_u8 v226, v226
	ds_read_u8 v227, v227
	ds_read_u8 v228, v228
	ds_read_u8 v229, v229
	ds_read_u8 v230, v230
	ds_read_u8 v231, v231
	ds_read_u8 v232, v232
	s_waitcnt lgkmcnt(8)
	v_lshl_add_u32 v224, v224, 2, v219
	s_waitcnt lgkmcnt(7)
	v_lshl_add_u32 v225, v225, 2, v219
	s_waitcnt lgkmcnt(6)
	v_lshl_add_u32 v226, v226, 2, v219
	s_waitcnt lgkmcnt(5)
	v_lshl_add_u32 v227, v227, 2, v219
	s_waitcnt lgkmcnt(4)
	v_lshl_add_u32 v228, v228, 2, v219
	s_waitcnt lgkmcnt(3)
	v_lshl_add_u32 v229, v229, 2, v219
	s_waitcnt lgkmcnt(2)
	v_lshl_add_u32 v230, v230, 2, v219
	s_waitcnt lgkmcnt(1)
	v_lshl_add_u32 v231, v231, 2, v219
	s_waitcnt lgkmcnt(0)
	v_lshl_add_u32 v232, v232, 2, v219
	ds_read_b32 v224, v224 offset:4096
	ds_read_b32 v225, v225 offset:4096
	ds_read_b32 v226, v226 offset:4096
	ds_read_b32 v227, v227 offset:4096
	ds_read_b32 v228, v228 offset:4096
	ds_read_b32 v229, v229 offset:4096
	ds_read_b32 v230, v230 offset:4096
	ds_read_b32 v231, v231 offset:4096
	ds_read_b32 v232, v232 offset:4096
	v_lshl_add_u32 v244, v246, 2, v242
	s_waitcnt lgkmcnt(8)
; DI void bias16(const unsigned char* blut, const float* tblh, const int (&dist)[16], float (&bv)[16]) {
;   int bk[16];
; #pragma unroll
;   for (int i = 0; i < 16; ++i) { const int d = dist[i] < 0 ? 0 : (dist[i] > 2048 ? 2048 : dist[i]); bk[i] = blut[d]; }
; #pragma unroll
;   for (int i = 0; i < 16; ++i) asm volatile("" : "+v"(bk[i]));
; #pragma unroll
;   for (int i = 0; i < 16; ++i) bv[i] = tblh[bk[i]];
; #pragma unroll
;   for (int i = 0; i < 16; ++i) asm volatile("" : "+v"(bv[i]));
; }
	ds_write_b32 v244, v224 offset:0
	s_waitcnt lgkmcnt(7)
	ds_write_b32 v244, v225 offset:256
	s_waitcnt lgkmcnt(6)
	ds_write_b32 v244, v226 offset:512
	s_waitcnt lgkmcnt(5)
	ds_write_b32 v244, v227 offset:768
	s_waitcnt lgkmcnt(4)
	ds_write_b32 v244, v228 offset:1024
	s_waitcnt lgkmcnt(3)
	ds_write_b32 v244, v229 offset:1280
	s_waitcnt lgkmcnt(2)
	ds_write_b32 v244, v230 offset:1536
	s_waitcnt lgkmcnt(1)
	ds_write_b32 v244, v231 offset:1792
	s_waitcnt lgkmcnt(0)
	ds_write_b32 v244, v232 offset:2048
	v_add_u32_e32 v224, 512, v246
	v_add_u32_e32 v225, 576, v246
	v_add_u32_e32 v226, 640, v246
	v_add_u32_e32 v227, 704, v246
	v_add_u32_e32 v228, 768, v246
	v_add_u32_e32 v229, 832, v246
	v_add_u32_e32 v230, 896, v246
	v_add_u32_e32 v231, 960, v246
	v_add_u32_e32 v232, 1024, v246
	ds_read_u8 v224, v224
	ds_read_u8 v225, v225
	ds_read_u8 v226, v226
	ds_read_u8 v227, v227
	ds_read_u8 v228, v228
	ds_read_u8 v229, v229
	ds_read_u8 v230, v230
	ds_read_u8 v231, v231
	ds_read_u8 v232, v232
	s_waitcnt lgkmcnt(8)
	v_lshl_add_u32 v224, v224, 2, v219
	s_waitcnt lgkmcnt(7)
	v_lshl_add_u32 v225, v225, 2, v219
	s_waitcnt lgkmcnt(6)
	v_lshl_add_u32 v226, v226, 2, v219
	s_waitcnt lgkmcnt(5)
	v_lshl_add_u32 v227, v227, 2, v219
	s_waitcnt lgkmcnt(4)
	v_lshl_add_u32 v228, v228, 2, v219
	s_waitcnt lgkmcnt(3)
	v_lshl_add_u32 v229, v229, 2, v219
	s_waitcnt lgkmcnt(2)
	v_lshl_add_u32 v230, v230, 2, v219
	s_waitcnt lgkmcnt(1)
	v_lshl_add_u32 v231, v231, 2, v219
	s_waitcnt lgkmcnt(0)
	v_lshl_add_u32 v232, v232, 2, v219
	ds_read_b32 v224, v224 offset:4096
	ds_read_b32 v225, v225 offset:4096
	ds_read_b32 v226, v226 offset:4096
	ds_read_b32 v227, v227 offset:4096
	ds_read_b32 v228, v228 offset:4096
	ds_read_b32 v229, v229 offset:4096
	ds_read_b32 v230, v230 offset:4096
	ds_read_b32 v231, v231 offset:4096
	ds_read_b32 v232, v232 offset:4096
	v_lshl_add_u32 v244, v246, 2, v242
	s_waitcnt lgkmcnt(8)
	ds_write_b32 v244, v224 offset:2304
	s_waitcnt lgkmcnt(7)
	ds_write_b32 v244, v225 offset:2560
	s_waitcnt lgkmcnt(6)
	ds_write_b32 v244, v226 offset:2816
	s_waitcnt lgkmcnt(5)
	ds_write_b32 v244, v227 offset:3072
	s_waitcnt lgkmcnt(4)
	ds_write_b32 v244, v228 offset:3328
	s_waitcnt lgkmcnt(3)
	ds_write_b32 v244, v229 offset:3584
	s_waitcnt lgkmcnt(2)
	ds_write_b32 v244, v230 offset:3840
	s_waitcnt lgkmcnt(1)
	ds_write_b32 v244, v231 offset:4096
	s_waitcnt lgkmcnt(0)
	ds_write_b32 v244, v232 offset:4352
	v_add_u32_e32 v224, 1088, v246
	v_add_u32_e32 v225, 1152, v246
	v_add_u32_e32 v226, 1216, v246
	v_add_u32_e32 v227, 1280, v246
	v_add_u32_e32 v228, 1344, v246
	v_add_u32_e32 v229, 1408, v246
	v_add_u32_e32 v230, 1472, v246
	v_add_u32_e32 v231, 1536, v246
	v_add_u32_e32 v232, 1600, v246
	ds_read_u8 v224, v224
	ds_read_u8 v225, v225
	ds_read_u8 v226, v226
	ds_read_u8 v227, v227
	ds_read_u8 v228, v228
	ds_read_u8 v229, v229
	ds_read_u8 v230, v230
	ds_read_u8 v231, v231
	ds_read_u8 v232, v232
	s_waitcnt lgkmcnt(8)
	v_lshl_add_u32 v224, v224, 2, v219
	s_waitcnt lgkmcnt(7)
	v_lshl_add_u32 v225, v225, 2, v219
	s_waitcnt lgkmcnt(6)
	v_lshl_add_u32 v226, v226, 2, v219
	s_waitcnt lgkmcnt(5)
	v_lshl_add_u32 v227, v227, 2, v219
	s_waitcnt lgkmcnt(4)
	v_lshl_add_u32 v228, v228, 2, v219
	s_waitcnt lgkmcnt(3)
	v_lshl_add_u32 v229, v229, 2, v219
	s_waitcnt lgkmcnt(2)
	v_lshl_add_u32 v230, v230, 2, v219
	s_waitcnt lgkmcnt(1)
	v_lshl_add_u32 v231, v231, 2, v219
	s_waitcnt lgkmcnt(0)
	v_lshl_add_u32 v232, v232, 2, v219
	ds_read_b32 v224, v224 offset:4096
	ds_read_b32 v225, v225 offset:4096
	ds_read_b32 v226, v226 offset:4096
	ds_read_b32 v227, v227 offset:4096
	ds_read_b32 v228, v228 offset:4096
	ds_read_b32 v229, v229 offset:4096
	ds_read_b32 v230, v230 offset:4096
	ds_read_b32 v231, v231 offset:4096
	ds_read_b32 v232, v232 offset:4096
	v_lshl_add_u32 v244, v246, 2, v242
	s_waitcnt lgkmcnt(8)
	ds_write_b32 v244, v224 offset:4608
	s_waitcnt lgkmcnt(7)
	ds_write_b32 v244, v225 offset:4864
	s_waitcnt lgkmcnt(6)
	ds_write_b32 v244, v226 offset:5120
	s_waitcnt lgkmcnt(5)
	ds_write_b32 v244, v227 offset:5376
	s_waitcnt lgkmcnt(4)
	ds_write_b32 v244, v228 offset:5632
	s_waitcnt lgkmcnt(3)
	ds_write_b32 v244, v229 offset:5888
	s_waitcnt lgkmcnt(2)
	ds_write_b32 v244, v230 offset:6144
	s_waitcnt lgkmcnt(1)
	ds_write_b32 v244, v231 offset:6400
	s_waitcnt lgkmcnt(0)
	ds_write_b32 v244, v232 offset:6656
	ds_read_b32 v240, v219 offset:4220
	v_add_u32_e32 v242, 148, v242
	v_mov_b32_e32 v243, 0x7f800000
	s_waitcnt lgkmcnt(0)

; #define MFMA32(a, b, c) __builtin_amdgcn_mfma_f32_32x32x16_bf16((a), (b), (c), 0, 0, 0)
; #define NEGINF (-__builtin_inff())
; #define TIDX get_tid_()
; DI float shx32(float v) { const auto r = __builtin_amdgcn_permlane32_swap(__float_as_uint(v), __float_as_uint(v), false, false); return __uint_as_float((threadIdx.x & 32) ? r[0] : r[1]); }
; DI void moba_item(const Params& p, int b, int hd, int qb, const unsigned char* blut, const float* tbl) {
;   const int lane = TIDX & 63, r = lane & 31, h = lane >> 5;
;   const int bh = b * 4 + hd;
;   const int t = qb * 32 + r;
;   const int c = qb >> 3;
;   const float* tblh = tbl + (6 + hd) * 32;
;   bf16x8 qf[4];
;   load_q(qf, (const bf16_t*)(p.ws + OFF_QM) + (size_t)(b * 4096 + t) * 256 + hd * 64 + 8 * h);
;   unsigned mmask = 0u;
;   if (c > 0) {
;     const bf16_t* km = (const bf16_t*)(p.ws + OFF_KMEAN) + (size_t)bh * 16 * 64 + (size_t)(r & 15) * 64 + 8 * h;
;     f32x16 s;
; #pragma unroll
;     for (int i = 0; i < 16; ++i) s[i] = 0.f;
; #pragma unroll
;     for (int ss = 0; ss < 4; ++ss) {
;       bf16x8 kf = *(const bf16x8*)(km + 16 * ss);
;       if (r >= 16) {
; #pragma unroll
;         for (int j = 0; j < 8; ++j) kf[j] = 0;
;       }
;       s = MFMA32(kf, qf[ss], s);
;     }
;     float g16[16];
; #pragma unroll
;     for (int i = 0; i < 8; ++i) {
;       const float own = s[i], oth = shx32(own);
;       const int base = (i & 3) + 8 * (i >> 2);
;       g16[base] = h ? oth : own;
;       g16[base + 4] = h ? own : oth;
;     }
; #pragma unroll
;     for (int n = 0; n < 16; ++n) g16[n] = (n < c) ? g16[n] : NEGINF;
.LfM_skip:
	s_or_b64 exec, exec, s[8:9]
	s_barrier
	ds_read_b32 v0, v0
	v_lshrrev_b32_e32 v1, 6, v129
	s_waitcnt lgkmcnt(0)
	v_add_u32_e32 v0, v0, v1
	s_movk_i32 s8, 0x200
	s_waitcnt lgkmcnt(0)
	v_cmp_gt_i32_e32 vcc, s8, v0
	s_mov_b64 s[8:9], -1
	s_and_saveexec_b64 s[54:55], vcc
	s_cbranch_execz .LBB0_934
	v_lshrrev_b32_e32 v1, 5, v0
	v_lshlrev_b32_e32 v1, 3, v1
	v_and_b32_e32 v21, 7, v0
	v_add_u32_e32 v1, v1, v21
	v_bfe_u32 v21, v0, 3, 2
	v_lshl_add_u32 v0, v1, 5, v21
	v_add_u32_e32 v0, s101, v0
	v_ashrrev_i32_e32 v1, 31, v0
	v_lshrrev_b32_e32 v1, 27, v1
	v_add_u32_e32 v1, v0, v1
	v_ashrrev_i32_e32 v21, 5, v1
	v_and_b32_e32 v1, 0xffffffe0, v1
	v_sub_u32_e32 v16, v0, v1
	v_mov_b32_e32 v0, v129
	v_sub_u32_e32 v154, 0x7f, v21
	v_lshlrev_b32_e32 v1, 10, v16
	v_and_b32_e32 v18, 31, v0
	v_bfe_u32 v19, v0, 5, 1
	v_lshl_or_b32 v0, v154, 5, v18
	v_and_b32_e32 v1, 0xfffff000, v1
	v_add_u32_e32 v132, v0, v1
	v_ashrrev_i32_e32 v133, 31, v132
	v_readlane_b32 s8, v253, 45
	v_and_b32_e32 v20, 3, v16
	v_lshlrev_b64 v[0:1], 9, v[132:133]
	v_readlane_b32 s9, v253, 46
	v_lshlrev_b32_e32 v130, 7, v20
	v_cmp_lt_u32_e32 vcc, 7, v154
	v_lshl_add_u64 v[0:1], s[8:9], 0, v[0:1]
	v_lshl_add_u64 v[0:1], v[0:1], 0, v[130:131]
	v_lshlrev_b32_e32 v130, 4, v19
	v_lshl_add_u64 v[0:1], v[0:1], 0, v[130:131]
	global_load_dwordx4 v[80:83], v[0:1], off
	global_load_dwordx4 v[84:87], v[0:1], off offset:32
	global_load_dwordx4 v[88:91], v[0:1], off offset:64
	global_load_dwordx4 v[92:95], v[0:1], off offset:96
	v_ashrrev_i32_e32 v17, 31, v16
	s_and_saveexec_b64 s[8:9], vcc
	s_xor_b64 s[8:9], exec, s[8:9]
	s_cbranch_execz .LBB0_942
	v_readlane_b32 s24, v253, 47
	v_lshlrev_b64 v[0:1], 11, v[16:17]
	v_readlane_b32 s25, v253, 48
	v_lshlrev_b32_e32 v3, 7, v18
	v_lshlrev_b32_e32 v2, 3, v19
	v_lshl_add_u64 v[0:1], s[24:25], 0, v[0:1]
	v_and_b32_e32 v130, 0x780, v3
	v_lshl_add_u64 v[0:1], v[0:1], 0, v[130:131]
	v_lshlrev_b32_e32 v130, 1, v2
	v_lshl_add_u64 v[26:27], v[0:1], 0, v[130:131]
	global_load_dwordx4 v[0:3], v[26:27], off
	global_load_dwordx4 v[22:25], v[26:27], off offset:32
	v_cmp_lt_u32_e32 vcc, 15, v18
	s_movk_i32 s23, 0x47
	s_waitcnt vmcnt(1)
	v_cndmask_b32_e64 v3, v3, 0, vcc
	v_cndmask_b32_e64 v2, v2, 0, vcc
	v_cndmask_b32_e64 v1, v1, 0, vcc
	v_cndmask_b32_e64 v0, v0, 0, vcc
	s_waitcnt vmcnt(0)
	v_cndmask_b32_e64 v25, v25, 0, vcc
	v_cndmask_b32_e64 v24, v24, 0, vcc
	v_mfma_f32_32x32x16_bf16 v[0:15], v[0:3], v[80:83], 0
	v_cndmask_b32_e64 v23, v23, 0, vcc
	v_cndmask_b32_e64 v22, v22, 0, vcc
	s_nop 1
	v_mfma_f32_32x32x16_bf16 v[0:15], v[22:25], v[84:87], v[0:15]
	global_load_dwordx4 v[22:25], v[26:27], off offset:64
	s_waitcnt vmcnt(0)
	v_cndmask_b32_e64 v25, v25, 0, vcc
	v_cndmask_b32_e64 v24, v24, 0, vcc
	v_cndmask_b32_e64 v23, v23, 0, vcc
	v_cndmask_b32_e64 v22, v22, 0, vcc
	s_nop 1
	v_mfma_f32_32x32x16_bf16 v[0:15], v[22:25], v[88:91], v[0:15]
	global_load_dwordx4 v[22:25], v[26:27], off offset:96
	s_waitcnt vmcnt(0)
	v_cndmask_b32_e64 v25, v25, 0, vcc
	v_cndmask_b32_e64 v24, v24, 0, vcc
	v_cndmask_b32_e64 v23, v23, 0, vcc
	v_cndmask_b32_e64 v22, v22, 0, vcc
	v_cmp_eq_u32_e32 vcc, 0, v19
	s_nop 0
	v_mfma_f32_32x32x16_bf16 v[0:15], v[22:25], v[92:95], v[0:15]
	s_nop 11
	v_mov_b32_e32 v8, v0
	v_mov_b32_e32 v9, v0
	s_nop 1
	v_permlane32_swap_b32_e32 v8, v9
	v_cndmask_b32_e64 v9, v8, v9, s[12:13]
	v_mov_b32_e32 v8, v1
	v_mov_b32_e32 v11, v1
	s_nop 1
	v_permlane32_swap_b32_e32 v8, v11
	v_cndmask_b32_e64 v8, v8, v11, s[12:13]
	v_cndmask_b32_e32 v11, v8, v1, vcc
	v_cndmask_b32_e32 v12, v1, v8, vcc
	v_mov_b32_e32 v1, v2
	v_mov_b32_e32 v8, v2
	s_nop 1
	v_permlane32_swap_b32_e32 v1, v8
	v_cndmask_b32_e64 v1, v1, v8, s[12:13]
	v_cndmask_b32_e32 v13, v1, v2, vcc
	v_cndmask_b32_e32 v14, v2, v1, vcc
	v_mov_b32_e32 v1, v3
	v_mov_b32_e32 v2, v3
	s_nop 1
	v_permlane32_swap_b32_e32 v1, v2
	v_cndmask_b32_e64 v1, v1, v2, s[12:13]
	v_cndmask_b32_e32 v15, v1, v3, vcc
	v_cndmask_b32_e32 v22, v3, v1, vcc
	v_mov_b32_e32 v1, v4
	v_mov_b32_e32 v2, v4
	s_nop 1
	v_permlane32_swap_b32_e32 v1, v2
	v_cndmask_b32_e64 v1, v1, v2, s[12:13]
	v_cndmask_b32_e32 v23, v1, v4, vcc
	v_cndmask_b32_e32 v24, v4, v1, vcc
	v_mov_b32_e32 v1, v5
	v_mov_b32_e32 v2, v5
	s_nop 1
	v_permlane32_swap_b32_e32 v1, v2
	v_cndmask_b32_e64 v1, v1, v2, s[12:13]
	v_cndmask_b32_e32 v25, v1, v5, vcc
	v_cndmask_b32_e32 v26, v5, v1, vcc
	v_mov_b32_e32 v1, v6
	v_mov_b32_e32 v2, v6
	s_nop 1
	v_permlane32_swap_b32_e32 v1, v2
	v_cndmask_b32_e64 v1, v1, v2, s[12:13]
	v_cndmask_b32_e32 v27, v1, v6, vcc
	v_cndmask_b32_e32 v28, v6, v1, vcc
	v_mov_b32_e32 v1, v7
	v_mov_b32_e32 v2, v7
	s_nop 1
	v_permlane32_swap_b32_e32 v1, v2
	v_cndmask_b32_e64 v1, v1, v2, s[12:13]
	v_cndmask_b32_e32 v10, v0, v9, vcc
	v_cndmask_b32_e32 v29, v1, v7, vcc
	v_cndmask_b32_e32 v8, v7, v1, vcc
	v_cndmask_b32_e32 v0, v9, v0, vcc
	v_cmp_lt_u32_e32 vcc, 15, v154
	s_nop 1
	v_cndmask_b32_e32 v1, v199, v11, vcc
	v_cmp_lt_u32_e32 vcc, 23, v154
	s_nop 1
	v_cndmask_b32_e32 v2, v199, v13, vcc
	v_cmp_lt_u32_e32 vcc, 31, v154
	s_nop 1
	v_cndmask_b32_e32 v3, v199, v15, vcc
	v_cmp_lt_u32_e32 vcc, 39, v154
	s_nop 1
	v_cndmask_b32_e32 v4, v199, v10, vcc
	v_cmp_lt_u32_e32 vcc, 47, v154
	s_nop 1
	v_cndmask_b32_e32 v5, v199, v12, vcc
	v_cmp_lt_u32_e32 vcc, 55, v154
	s_nop 1
	v_cndmask_b32_e32 v6, v199, v14, vcc
	v_cmp_lt_u32_e32 vcc, 63, v154
	s_nop 1
	v_cndmask_b32_e32 v7, v199, v22, vcc
	v_cmp_lt_u32_e32 vcc, s23, v154
	s_movk_i32 s23, 0x4f
	s_nop 0
	v_cndmask_b32_e32 v9, v199, v23, vcc
	v_cmp_lt_u32_e32 vcc, s23, v154
	s_movk_i32 s23, 0x57
	s_nop 0
	v_cndmask_b32_e32 v10, v199, v25, vcc
	v_cmp_lt_u32_e32 vcc, s23, v154
	s_movk_i32 s23, 0x5f
	s_nop 0
	v_cndmask_b32_e32 v11, v199, v27, vcc
; #define NEGINF (-__builtin_inff())
; DI void moba_item(const Params& p, int b, int hd, int qb, const unsigned char* blut, const float* tbl) {
;     ...
; #pragma unroll
;     for (int n = 0; n < 16; ++n) g16[n] = (n < c) ? g16[n] : NEGINF;
; #pragma unroll
;     for (int round = 0; round < 3; ++round) {
;       float best = NEGINF; int bi = -1;
; #pragma unroll
;       for (int n = 0; n < 16; ++n) if (g16[n] > best) { best = g16[n]; bi = n; }
;       if (bi >= 0) mmask |= 1u << bi;
; #pragma unroll
;       for (int n = 0; n < 16; ++n) if (n == bi) g16[n] = NEGINF;
;     }
	v_cmp_lt_u32_e32 vcc, s23, v154
	s_movk_i32 s23, 0x67
	s_nop 0
	v_cndmask_b32_e32 v12, v199, v29, vcc
	v_cmp_lt_u32_e32 vcc, s23, v154
	s_movk_i32 s23, 0x6f
	s_nop 0
	v_cndmask_b32_e32 v13, v199, v24, vcc
	v_cmp_lt_u32_e32 vcc, s23, v154
	s_movk_i32 s23, 0x77
	s_nop 0
	v_cndmask_b32_e32 v14, v199, v26, vcc
	v_cmp_lt_u32_e32 vcc, s23, v154
	s_movk_i32 s23, 0x7f
	s_nop 0
	v_cndmask_b32_e32 v15, v199, v28, vcc
	v_cmp_lt_u32_e32 vcc, s23, v154
	s_nop 1
	v_cndmask_b32_e32 v8, v199, v8, vcc
	v_cmp_nlg_f32_e32 vcc, s5, v0
	s_nop 1
	v_cndmask_b32_e32 v22, v0, v199, vcc
	v_cndmask_b32_e64 v23, 0, -1, vcc
	v_cmp_gt_f32_e32 vcc, v1, v22
	s_nop 1
	v_cndmask_b32_e32 v22, v22, v1, vcc
	v_cndmask_b32_e64 v23, v23, 1, vcc
	v_cmp_gt_f32_e32 vcc, v2, v22
	s_nop 1
	v_cndmask_b32_e32 v22, v22, v2, vcc
	v_cndmask_b32_e64 v23, v23, 2, vcc
	v_cmp_gt_f32_e32 vcc, v3, v22
	s_nop 1
	v_cndmask_b32_e32 v22, v22, v3, vcc
	v_cndmask_b32_e64 v23, v23, 3, vcc
	v_cmp_gt_f32_e32 vcc, v4, v22
	s_nop 1
	v_cndmask_b32_e32 v22, v22, v4, vcc
	v_cndmask_b32_e64 v23, v23, 4, vcc
	v_cmp_gt_f32_e32 vcc, v5, v22
	s_nop 1
	v_cndmask_b32_e32 v22, v22, v5, vcc
	v_cndmask_b32_e64 v23, v23, 5, vcc
	v_cmp_gt_f32_e32 vcc, v6, v22
	s_nop 1
	v_cndmask_b32_e32 v22, v22, v6, vcc
	v_cndmask_b32_e64 v23, v23, 6, vcc
	v_cmp_gt_f32_e32 vcc, v7, v22
	s_nop 1
	v_cndmask_b32_e32 v22, v22, v7, vcc
	v_cndmask_b32_e64 v23, v23, 7, vcc
	v_cmp_gt_f32_e32 vcc, v9, v22
	s_nop 1
	v_cndmask_b32_e32 v22, v22, v9, vcc
	v_cndmask_b32_e64 v23, v23, 8, vcc
	v_cmp_gt_f32_e32 vcc, v10, v22
	s_nop 1
	v_cndmask_b32_e32 v22, v22, v10, vcc
	v_cndmask_b32_e64 v23, v23, 9, vcc
	v_cmp_gt_f32_e32 vcc, v11, v22
	s_nop 1
	v_cndmask_b32_e32 v22, v22, v11, vcc
	v_cndmask_b32_e64 v23, v23, 10, vcc
	v_cmp_gt_f32_e32 vcc, v12, v22
	s_nop 1
	v_cndmask_b32_e32 v22, v22, v12, vcc
	v_cndmask_b32_e64 v23, v23, 11, vcc
	v_cmp_gt_f32_e32 vcc, v13, v22
	s_nop 1
	v_cndmask_b32_e32 v22, v22, v13, vcc
	v_cndmask_b32_e64 v23, v23, 12, vcc
	v_cmp_gt_f32_e32 vcc, v14, v22
	s_nop 1
	v_cndmask_b32_e32 v22, v22, v14, vcc
	v_cndmask_b32_e64 v23, v23, 13, vcc
	v_cmp_gt_f32_e32 vcc, v15, v22
	s_nop 1
	v_cndmask_b32_e32 v22, v22, v15, vcc
	v_cndmask_b32_e64 v23, v23, 14, vcc
	v_cmp_ngt_f32_e32 vcc, v8, v22
	s_nop 1
	v_cndmask_b32_e32 v22, 15, v23, vcc
	v_lshlrev_b32_e64 v23, v22, 1
	v_cmp_lt_i32_e32 vcc, -1, v22
	s_nop 1
	v_cndmask_b32_e32 v23, 0, v23, vcc
	v_cmp_ne_u32_e32 vcc, 0, v22
	s_nop 1
	v_cndmask_b32_e32 v0, v199, v0, vcc
	v_cmp_ne_u32_e32 vcc, 1, v22
	s_nop 1
	v_cndmask_b32_e32 v1, v199, v1, vcc
	v_cmp_ne_u32_e32 vcc, 2, v22
	s_nop 1
	v_cndmask_b32_e32 v2, v199, v2, vcc
	v_cmp_ne_u32_e32 vcc, 3, v22
	s_nop 1
	v_cndmask_b32_e32 v3, v199, v3, vcc
	v_cmp_ne_u32_e32 vcc, 4, v22
	s_nop 1
	v_cndmask_b32_e32 v4, v199, v4, vcc
	v_cmp_ne_u32_e32 vcc, 5, v22
	s_nop 1
	v_cndmask_b32_e32 v5, v199, v5, vcc
	v_cmp_ne_u32_e32 vcc, 6, v22
	s_nop 1
	v_cndmask_b32_e32 v6, v199, v6, vcc
	v_cmp_ne_u32_e32 vcc, 7, v22
	s_nop 1
	v_cndmask_b32_e32 v7, v199, v7, vcc
	v_cmp_ne_u32_e32 vcc, 8, v22
	s_nop 1
	v_cndmask_b32_e32 v9, v199, v9, vcc
	v_cmp_ne_u32_e32 vcc, 9, v22
	s_nop 1
	v_cndmask_b32_e32 v10, v199, v10, vcc
	v_cmp_ne_u32_e32 vcc, 10, v22
	s_nop 1
	v_cndmask_b32_e32 v11, v199, v11, vcc
	v_cmp_ne_u32_e32 vcc, 11, v22
	s_nop 1
	v_cndmask_b32_e32 v12, v199, v12, vcc
	v_cmp_ne_u32_e32 vcc, 12, v22
	s_nop 1
	v_cndmask_b32_e32 v13, v199, v13, vcc
	v_cmp_ne_u32_e32 vcc, 13, v22
	s_nop 1
	v_cndmask_b32_e32 v14, v199, v14, vcc
	v_cmp_ne_u32_e32 vcc, 14, v22
	s_nop 1
	v_cndmask_b32_e32 v15, v199, v15, vcc
	v_cmp_ne_u32_e32 vcc, 15, v22
	s_nop 1
	v_cndmask_b32_e32 v8, v199, v8, vcc
	v_cmp_nlg_f32_e32 vcc, s5, v0
	s_nop 1
	v_cndmask_b32_e32 v22, v0, v199, vcc
	v_cndmask_b32_e64 v24, 0, -1, vcc
	v_cmp_gt_f32_e32 vcc, v1, v22
	s_nop 1
	v_cndmask_b32_e32 v22, v22, v1, vcc
	v_cndmask_b32_e64 v24, v24, 1, vcc
	v_cmp_gt_f32_e32 vcc, v2, v22
	s_nop 1
	v_cndmask_b32_e32 v22, v22, v2, vcc
	v_cndmask_b32_e64 v24, v24, 2, vcc
	v_cmp_gt_f32_e32 vcc, v3, v22
	s_nop 1
	v_cndmask_b32_e32 v22, v22, v3, vcc
	v_cndmask_b32_e64 v24, v24, 3, vcc
	v_cmp_gt_f32_e32 vcc, v4, v22
	s_nop 1
	v_cndmask_b32_e32 v22, v22, v4, vcc
	v_cndmask_b32_e64 v24, v24, 4, vcc
	v_cmp_gt_f32_e32 vcc, v5, v22
	s_nop 1
	v_cndmask_b32_e32 v22, v22, v5, vcc
	v_cndmask_b32_e64 v24, v24, 5, vcc
; #define NEGINF (-__builtin_inff())
; DI void moba_item(const Params& p, int b, int hd, int qb, const unsigned char* blut, const float* tbl) {
;     ...
;     for (int round = 0; round < 3; ++round) {
;       float best = NEGINF; int bi = -1;
; #pragma unroll
;       for (int n = 0; n < 16; ++n) if (g16[n] > best) { best = g16[n]; bi = n; }
;       if (bi >= 0) mmask |= 1u << bi;
; #pragma unroll
;       for (int n = 0; n < 16; ++n) if (n == bi) g16[n] = NEGINF;
;     }
;   }
;   mmask |= 1u << c;
	v_cmp_gt_f32_e32 vcc, v6, v22
	s_nop 1
	v_cndmask_b32_e32 v22, v22, v6, vcc
	v_cndmask_b32_e64 v24, v24, 6, vcc
	v_cmp_gt_f32_e32 vcc, v7, v22
	s_nop 1
	v_cndmask_b32_e32 v22, v22, v7, vcc
	v_cndmask_b32_e64 v24, v24, 7, vcc
	v_cmp_gt_f32_e32 vcc, v9, v22
	s_nop 1
	v_cndmask_b32_e32 v22, v22, v9, vcc
	v_cndmask_b32_e64 v24, v24, 8, vcc
	v_cmp_gt_f32_e32 vcc, v10, v22
	s_nop 1
	v_cndmask_b32_e32 v22, v22, v10, vcc
	v_cndmask_b32_e64 v24, v24, 9, vcc
	v_cmp_gt_f32_e32 vcc, v11, v22
	s_nop 1
	v_cndmask_b32_e32 v22, v22, v11, vcc
	v_cndmask_b32_e64 v24, v24, 10, vcc
	v_cmp_gt_f32_e32 vcc, v12, v22
	s_nop 1
	v_cndmask_b32_e32 v22, v22, v12, vcc
	v_cndmask_b32_e64 v24, v24, 11, vcc
	v_cmp_gt_f32_e32 vcc, v13, v22
	s_nop 1
	v_cndmask_b32_e32 v22, v22, v13, vcc
	v_cndmask_b32_e64 v24, v24, 12, vcc
	v_cmp_gt_f32_e32 vcc, v14, v22
	s_nop 1
	v_cndmask_b32_e32 v22, v22, v14, vcc
	v_cndmask_b32_e64 v24, v24, 13, vcc
	v_cmp_gt_f32_e32 vcc, v15, v22
	s_nop 1
	v_cndmask_b32_e32 v22, v22, v15, vcc
	v_cndmask_b32_e64 v24, v24, 14, vcc
	v_cmp_ngt_f32_e32 vcc, v8, v22
	s_nop 1
	v_cndmask_b32_e32 v22, 15, v24, vcc
	v_lshlrev_b32_e64 v24, v22, 1
	v_cmp_lt_i32_e32 vcc, -1, v22
	s_nop 1
	v_cndmask_b32_e32 v24, 0, v24, vcc
	v_cmp_ne_u32_e32 vcc, 0, v22
	s_nop 1
	v_cndmask_b32_e32 v0, v199, v0, vcc
	v_cmp_ne_u32_e32 vcc, 1, v22
	s_nop 1
	v_cndmask_b32_e32 v1, v199, v1, vcc
	v_cmp_ne_u32_e32 vcc, 2, v22
	s_nop 1
	v_cndmask_b32_e32 v2, v199, v2, vcc
	v_cmp_ne_u32_e32 vcc, 3, v22
	s_nop 1
	v_cndmask_b32_e32 v3, v199, v3, vcc
	v_cmp_ne_u32_e32 vcc, 4, v22
	s_nop 1
	v_cndmask_b32_e32 v4, v199, v4, vcc
	v_cmp_ne_u32_e32 vcc, 5, v22
	s_nop 1
	v_cndmask_b32_e32 v5, v199, v5, vcc
	v_cmp_ne_u32_e32 vcc, 6, v22
	s_nop 1
	v_cndmask_b32_e32 v6, v199, v6, vcc
	v_cmp_ne_u32_e32 vcc, 7, v22
	s_nop 1
	v_cndmask_b32_e32 v7, v199, v7, vcc
	v_cmp_ne_u32_e32 vcc, 8, v22
	s_nop 1
	v_cndmask_b32_e32 v9, v199, v9, vcc
	v_cmp_ne_u32_e32 vcc, 9, v22
	s_nop 1
	v_cndmask_b32_e32 v10, v199, v10, vcc
	v_cmp_ne_u32_e32 vcc, 10, v22
	s_nop 1
	v_cndmask_b32_e32 v11, v199, v11, vcc
	v_cmp_ne_u32_e32 vcc, 11, v22
	s_nop 1
	v_cndmask_b32_e32 v12, v199, v12, vcc
	v_cmp_ne_u32_e32 vcc, 12, v22
	s_nop 1
	v_cndmask_b32_e32 v13, v199, v13, vcc
	v_cmp_ne_u32_e32 vcc, 13, v22
	s_nop 1
	v_cndmask_b32_e32 v14, v199, v14, vcc
	v_cmp_ne_u32_e32 vcc, 14, v22
	s_nop 1
	v_cndmask_b32_e32 v15, v199, v15, vcc
	v_cmp_ne_u32_e32 vcc, 15, v22
	s_nop 1
	v_cndmask_b32_e32 v8, v199, v8, vcc
	v_cmp_nlg_f32_e32 vcc, s5, v0
	s_nop 1
	v_cndmask_b32_e32 v0, v0, v199, vcc
	v_cndmask_b32_e64 v22, 0, -1, vcc
	v_cmp_gt_f32_e32 vcc, v1, v0
	s_nop 1
	v_cndmask_b32_e32 v0, v0, v1, vcc
	v_cndmask_b32_e64 v1, v22, 1, vcc
	v_cmp_gt_f32_e32 vcc, v2, v0
	s_nop 1
	v_cndmask_b32_e32 v0, v0, v2, vcc
	v_cndmask_b32_e64 v1, v1, 2, vcc
	v_cmp_gt_f32_e32 vcc, v3, v0
	s_nop 1
	v_cndmask_b32_e32 v0, v0, v3, vcc
	v_cndmask_b32_e64 v1, v1, 3, vcc
	v_cmp_gt_f32_e32 vcc, v4, v0
	s_nop 1
	v_cndmask_b32_e32 v0, v0, v4, vcc
	v_cndmask_b32_e64 v1, v1, 4, vcc
	v_cmp_gt_f32_e32 vcc, v5, v0
	s_nop 1
	v_cndmask_b32_e32 v0, v0, v5, vcc
	v_cndmask_b32_e64 v1, v1, 5, vcc
	v_cmp_gt_f32_e32 vcc, v6, v0
	s_nop 1
	v_cndmask_b32_e32 v0, v0, v6, vcc
	v_cndmask_b32_e64 v1, v1, 6, vcc
	v_cmp_gt_f32_e32 vcc, v7, v0
	s_nop 1
	v_cndmask_b32_e32 v0, v0, v7, vcc
	v_cndmask_b32_e64 v1, v1, 7, vcc
	v_cmp_gt_f32_e32 vcc, v9, v0
	s_nop 1
	v_cndmask_b32_e32 v0, v0, v9, vcc
	v_cndmask_b32_e64 v1, v1, 8, vcc
	v_cmp_gt_f32_e32 vcc, v10, v0
	s_nop 1
	v_cndmask_b32_e32 v0, v0, v10, vcc
	v_cndmask_b32_e64 v1, v1, 9, vcc
	v_cmp_gt_f32_e32 vcc, v11, v0
	s_nop 1
	v_cndmask_b32_e32 v0, v0, v11, vcc
	v_cndmask_b32_e64 v1, v1, 10, vcc
	v_cmp_gt_f32_e32 vcc, v12, v0
	s_nop 1
	v_cndmask_b32_e32 v0, v0, v12, vcc
	v_cndmask_b32_e64 v1, v1, 11, vcc
	v_cmp_gt_f32_e32 vcc, v13, v0
	s_nop 1
	v_cndmask_b32_e32 v0, v0, v13, vcc
	v_cndmask_b32_e64 v1, v1, 12, vcc
	v_cmp_gt_f32_e32 vcc, v14, v0
	s_nop 1
	v_cndmask_b32_e32 v0, v0, v14, vcc
	v_cndmask_b32_e64 v1, v1, 13, vcc
	v_cmp_gt_f32_e32 vcc, v15, v0
	s_nop 1
	v_cndmask_b32_e32 v0, v0, v15, vcc
	v_cndmask_b32_e64 v1, v1, 14, vcc
	v_cmp_ngt_f32_e32 vcc, v8, v0
	s_nop 1
	v_cndmask_b32_e32 v0, 15, v1, vcc
	v_lshlrev_b32_e64 v1, v0, 1
	v_cmp_lt_i32_e32 vcc, -1, v0
	s_nop 1
	v_cndmask_b32_e32 v0, 0, v1, vcc
	v_or3_b32 v0, v24, v23, v0
